# GDN derive: the eight LDS reads of each conv block issued together with counted waits (on top of the LDS-DMA versions)
# speedup vs baseline: 1.0024x; 1.0024x over previous
; #define LAS __attribute__((address_space(3)))
; DI float siluf_(float x) { return x * frcp(1.f + __expf(-x)); }
; DI f32x4 gd_conv4(const LAS float* CW, const LAS float* RAW, int dt, int cc) {
;     f32x4 a = {0.f, 0.f, 0.f, 0.f};
; #pragma unroll
;     for (int j = 0; j < 4; ++j) a += *(const LAS f32x4*)(CW + j * 320 + cc) * *(const LAS f32x4*)(RAW + (dt + j) * 320 + cc);
; #pragma unroll
;     for (int i = 0; i < 4; ++i) a[i] = siluf_(a[i]);
;     return a;
; }
.Lgdn_top_done:
	ds_read_b128 v[208:211], v111
	ds_read_b128 v[212:215], v162
	ds_read_b128 v[216:219], v111 offset:1280
	ds_read_b128 v[220:223], v162 offset:1280
	ds_read_b128 v[224:227], v111 offset:2560
	ds_read_b128 v[228:231], v162 offset:2560
	ds_read_b128 v[72:75], v111 offset:3840
	ds_read_b128 v[76:79], v162 offset:3840
	s_waitcnt lgkmcnt(6)
	v_pk_fma_f32 v[80:81], v[210:211], v[214:215], 0 op_sel_hi:[1,1,0]
	v_pk_fma_f32 v[100:101], v[208:209], v[212:213], 0 op_sel_hi:[1,1,0]
	s_waitcnt lgkmcnt(4)
	v_pk_fma_f32 v[80:81], v[218:219], v[222:223], v[80:81]
	v_pk_fma_f32 v[100:101], v[216:217], v[220:221], v[100:101]
	s_waitcnt lgkmcnt(2)
	v_pk_fma_f32 v[80:81], v[226:227], v[230:231], v[80:81]
	v_pk_fma_f32 v[100:101], v[224:225], v[228:229], v[100:101]
	s_waitcnt lgkmcnt(0)
	v_pk_fma_f32 v[72:73], v[72:73], v[76:77], v[100:101]
	s_nop 0
	v_mul_f32_e32 v76, 0xbfb8aa3b, v72
	v_mul_f32_e32 v77, 0xbfb8aa3b, v73
	v_exp_f32_e32 v76, v76
	v_exp_f32_e32 v77, v77
	v_pk_fma_f32 v[74:75], v[74:75], v[78:79], v[80:81]
	v_add_f32_e32 v76, 1.0, v76
	v_add_f32_e32 v77, 1.0, v77
	v_rcp_f32_e32 v76, v76
	v_rcp_f32_e32 v77, v77
	s_nop 0
	v_pk_mul_f32 v[72:73], v[72:73], v[76:77]
	v_mul_f32_e32 v76, 0xbfb8aa3b, v74
	v_mul_f32_e32 v77, 0xbfb8aa3b, v75
	v_exp_f32_e32 v76, v76
	v_exp_f32_e32 v77, v77
	v_add_f32_e32 v76, 1.0, v76
	v_add_f32_e32 v77, 1.0, v77
	v_rcp_f32_e32 v76, v76
	v_rcp_f32_e32 v77, v77
	s_nop 0
	v_pk_mul_f32 v[74:75], v[74:75], v[76:77]
	ds_read_b128 v[208:211], v112
	ds_read_b128 v[212:215], v113
	ds_read_b128 v[216:219], v112 offset:1280
	ds_read_b128 v[220:223], v113 offset:1280
	ds_read_b128 v[224:227], v112 offset:2560
	ds_read_b128 v[228:231], v113 offset:2560
	ds_read_b128 v[76:79], v112 offset:3840
	ds_read_b128 v[100:103], v113 offset:3840
	s_waitcnt lgkmcnt(6)
	v_pk_fma_f32 v[80:81], v[210:211], v[214:215], 0 op_sel_hi:[1,1,0]
	v_pk_fma_f32 v[104:105], v[208:209], v[212:213], 0 op_sel_hi:[1,1,0]
	s_waitcnt lgkmcnt(4)
	v_pk_fma_f32 v[80:81], v[218:219], v[222:223], v[80:81]
	v_pk_fma_f32 v[104:105], v[216:217], v[220:221], v[104:105]
	s_waitcnt lgkmcnt(2)
	v_pk_fma_f32 v[80:81], v[226:227], v[230:231], v[80:81]
	v_pk_fma_f32 v[104:105], v[224:225], v[228:229], v[104:105]
	s_waitcnt lgkmcnt(0)
	v_pk_fma_f32 v[76:77], v[76:77], v[100:101], v[104:105]
	v_pk_fma_f32 v[78:79], v[78:79], v[102:103], v[80:81]
	v_mul_f32_e32 v80, 0xbfb8aa3b, v76
	v_mul_f32_e32 v81, 0xbfb8aa3b, v77
	v_exp_f32_e32 v80, v80
	v_exp_f32_e32 v81, v81
	ds_read_b128 v[208:211], v114
	ds_read_b128 v[212:215], v115
	ds_read_b128 v[216:219], v114 offset:1280
	ds_read_b128 v[220:223], v115 offset:1280
	ds_read_b128 v[224:227], v114 offset:2560
	ds_read_b128 v[228:231], v115 offset:2560
	ds_read_b128 v[100:103], v114 offset:3840
	ds_read_b128 v[190:193], v115 offset:3840
	v_add_f32_e32 v80, 1.0, v80
	v_add_f32_e32 v81, 1.0, v81
	v_rcp_f32_e32 v80, v80
	v_rcp_f32_e32 v81, v81
	s_waitcnt lgkmcnt(6)
	v_pk_fma_f32 v[104:105], v[208:209], v[212:213], 0 op_sel_hi:[1,1,0]
	v_pk_mul_f32 v[76:77], v[76:77], v[80:81]
	v_mul_f32_e32 v80, 0xbfb8aa3b, v78
	v_mul_f32_e32 v81, 0xbfb8aa3b, v79
	v_exp_f32_e32 v80, v80
	v_exp_f32_e32 v81, v81
	v_add_f32_e32 v80, 1.0, v80
	v_add_f32_e32 v81, 1.0, v81
	v_rcp_f32_e32 v80, v80
	v_rcp_f32_e32 v81, v81
	s_nop 0
	v_pk_mul_f32 v[78:79], v[78:79], v[80:81]
	v_pk_fma_f32 v[80:81], v[210:211], v[214:215], 0 op_sel_hi:[1,1,0]
	s_waitcnt lgkmcnt(4)
	v_pk_fma_f32 v[80:81], v[218:219], v[222:223], v[80:81]
	v_pk_fma_f32 v[104:105], v[216:217], v[220:221], v[104:105]
	s_waitcnt lgkmcnt(2)
	v_pk_fma_f32 v[80:81], v[226:227], v[230:231], v[80:81]
	v_pk_fma_f32 v[104:105], v[224:225], v[228:229], v[104:105]
	s_waitcnt lgkmcnt(0)
	v_pk_fma_f32 v[102:103], v[102:103], v[192:193], v[80:81]
	v_pk_fma_f32 v[80:81], v[100:101], v[190:191], v[104:105]
	s_nop 0
	v_mul_f32_e32 v100, 0xbfb8aa3b, v80
	v_mul_f32_e32 v101, 0xbfb8aa3b, v81
	v_exp_f32_e32 v100, v100
	v_exp_f32_e32 v101, v101
	v_add_f32_e32 v100, 1.0, v100
	v_add_f32_e32 v101, 1.0, v101
	v_rcp_f32_e32 v100, v100
	v_rcp_f32_e32 v101, v101
	s_nop 0
	v_pk_mul_f32 v[80:81], v[80:81], v[100:101]
	v_mul_f32_e32 v100, 0xbfb8aa3b, v102
	v_mul_f32_e32 v101, 0xbfb8aa3b, v103
	v_exp_f32_e32 v100, v100
	v_exp_f32_e32 v101, v101
	v_add_f32_e32 v100, 1.0, v100
	v_add_f32_e32 v101, 1.0, v101
	v_rcp_f32_e32 v100, v100
	v_rcp_f32_e32 v101, v101
	s_nop 0
	v_pk_mul_f32 v[100:101], v[102:103], v[100:101]
	ds_read_b128 v[208:211], v116
	ds_read_b128 v[212:215], v117
	ds_read_b128 v[216:219], v116 offset:1280
	ds_read_b128 v[220:223], v117 offset:1280
	ds_read_b128 v[224:227], v116 offset:2560
	ds_read_b128 v[228:231], v117 offset:2560
	ds_read_b128 v[102:105], v116 offset:3840
	ds_read_b128 v[190:193], v117 offset:3840
	s_waitcnt lgkmcnt(6)
	v_pk_fma_f32 v[130:131], v[210:211], v[214:215], 0 op_sel_hi:[1,1,0]
	v_pk_fma_f32 v[194:195], v[208:209], v[212:213], 0 op_sel_hi:[1,1,0]
	s_waitcnt lgkmcnt(4)
	v_pk_fma_f32 v[130:131], v[218:219], v[222:223], v[130:131]
	v_pk_fma_f32 v[194:195], v[216:217], v[220:221], v[194:195]
	s_waitcnt lgkmcnt(2)
	v_pk_fma_f32 v[130:131], v[226:227], v[230:231], v[130:131]
	v_pk_fma_f32 v[194:195], v[224:225], v[228:229], v[194:195]
	s_waitcnt lgkmcnt(0)
	v_pk_fma_f32 v[102:103], v[102:103], v[190:191], v[194:195]
	s_nop 0
	v_mul_f32_e32 v106, 0xbfb8aa3b, v102
	v_exp_f32_e32 v106, v106
	v_pk_fma_f32 v[104:105], v[104:105], v[192:193], v[130:131]
	ds_read_b128 v[208:211], v118
	ds_read_b128 v[212:215], v119
	ds_read_b128 v[216:219], v118 offset:1280
	ds_read_b128 v[220:223], v119 offset:1280
	ds_read_b128 v[224:227], v118 offset:2560
	ds_read_b128 v[228:231], v119 offset:2560
	ds_read_b128 v[190:193], v118 offset:3840
	ds_read_b128 v[194:197], v119 offset:3840
	v_add_f32_e32 v106, 1.0, v106
	v_rcp_f32_e32 v130, v106
	v_mul_f32_e32 v106, 0xbfb8aa3b, v103
	v_exp_f32_e32 v106, v106
	s_waitcnt lgkmcnt(6)
	v_pk_fma_f32 v[198:199], v[208:209], v[212:213], 0 op_sel_hi:[1,1,0]
	v_add_f32_e32 v106, 1.0, v106
	v_rcp_f32_e32 v131, v106
	v_mul_f32_e32 v106, 0xbfb8aa3b, v104
	v_exp_f32_e32 v106, v106
	v_pk_mul_f32 v[102:103], v[102:103], v[130:131]
	v_add_f32_e32 v106, 1.0, v106
	v_rcp_f32_e32 v130, v106
	v_mul_f32_e32 v106, 0xbfb8aa3b, v105
	v_exp_f32_e32 v106, v106
	s_nop 0
	v_add_f32_e32 v106, 1.0, v106
	v_rcp_f32_e32 v131, v106
	s_nop 0
	v_pk_mul_f32 v[104:105], v[104:105], v[130:131]
	v_pk_fma_f32 v[130:131], v[210:211], v[214:215], 0 op_sel_hi:[1,1,0]
	s_waitcnt lgkmcnt(4)
	v_pk_fma_f32 v[130:131], v[218:219], v[222:223], v[130:131]
	v_pk_fma_f32 v[198:199], v[216:217], v[220:221], v[198:199]
	s_waitcnt lgkmcnt(2)
	v_pk_fma_f32 v[130:131], v[226:227], v[230:231], v[130:131]
	v_pk_fma_f32 v[198:199], v[224:225], v[228:229], v[198:199]
	s_waitcnt lgkmcnt(0)
	v_pk_fma_f32 v[190:191], v[190:191], v[194:195], v[198:199]
	s_nop 0
	v_mul_f32_e32 v106, 0xbfb8aa3b, v190
	v_exp_f32_e32 v106, v106
	v_pk_fma_f32 v[130:131], v[192:193], v[196:197], v[130:131]
	v_mov_b32_e32 v196, v75
	v_mov_b32_e32 v197, v79
	v_add_f32_e32 v106, 1.0, v106
	v_rcp_f32_e32 v194, v106
	v_mul_f32_e32 v106, 0xbfb8aa3b, v191
	v_exp_f32_e32 v106, v106
	v_pk_mul_f32 v[196:197], v[196:197], v[196:197]
	v_add_f32_e32 v106, 1.0, v106
	v_rcp_f32_e32 v195, v106
	v_mul_f32_e32 v106, 0xbfb8aa3b, v130
	v_exp_f32_e32 v106, v106
	v_pk_mul_f32 v[190:191], v[190:191], v[194:195]
	v_mov_b32_e32 v194, v73
	v_add_f32_e32 v106, 1.0, v106
	v_rcp_f32_e32 v192, v106
	v_mul_f32_e32 v106, 0xbfb8aa3b, v131
	v_exp_f32_e32 v106, v106
	v_mov_b32_e32 v195, v77
	v_pk_mul_f32 v[194:195], v[194:195], v[194:195]
	v_add_f32_e32 v106, 1.0, v106
	v_rcp_f32_e32 v193, v106
	s_nop 0
	v_pk_mul_f32 v[192:193], v[130:131], v[192:193]
	v_mov_b32_e32 v130, v72
	v_mov_b32_e32 v131, v76
	v_pk_fma_f32 v[130:131], v[130:131], v[130:131], v[194:195]
	v_mov_b32_e32 v194, v74
	v_mov_b32_e32 v195, v78
	v_pk_fma_f32 v[194:195], v[194:195], v[194:195], v[196:197]
	v_mov_b32_e32 v196, v101
	v_pk_add_f32 v[130:131], v[130:131], v[194:195]
	v_mov_b32_e32 v194, v81
	v_mov_b32_e32 v195, v103
	v_add_f32_e32 v106, v130, v131
	v_mov_b32_e32 v130, v80
	v_mov_b32_e32 v131, v102
	v_pk_mul_f32 v[194:195], v[194:195], v[194:195]
	v_mov_b32_e32 v197, v105
	v_pk_fma_f32 v[130:131], v[130:131], v[130:131], v[194:195]
	v_mov_b32_e32 v194, v100
	v_mov_b32_e32 v195, v104
	v_pk_mul_f32 v[196:197], v[196:197], v[196:197]
	v_add_f32_dpp v106, v106, v106 quad_perm:[1,0,3,2] row_mask:0xf bank_mask:0xf bound_ctrl:1
	v_pk_fma_f32 v[194:195], v[194:195], v[194:195], v[196:197]
	s_nop 0
	v_pk_add_f32 v[130:131], v[130:131], v[194:195]
	v_add_f32_dpp v106, v106, v106 quad_perm:[2,3,0,1] row_mask:0xf bank_mask:0xf bound_ctrl:1
	v_add_f32_e32 v128, v130, v131
	s_nop 0
	v_add_f32_dpp v106, v106, v106 row_half_mirror row_mask:0xf bank_mask:0xf bound_ctrl:1
	v_add_f32_dpp v128, v128, v128 quad_perm:[1,0,3,2] row_mask:0xf bank_mask:0xf bound_ctrl:1
	s_nop 0
	v_add_f32_dpp v106, v106, v106 row_ror:8 row_mask:0xf bank_mask:0xf bound_ctrl:1
	v_add_f32_dpp v128, v128, v128 quad_perm:[2,3,0,1] row_mask:0xf bank_mask:0xf bound_ctrl:1
	v_add_f32_e32 v106, 0x358637bd, v106
	v_rsq_f32_e32 v106, v106
	v_add_f32_dpp v128, v128, v128 row_half_mirror row_mask:0xf bank_mask:0xf bound_ctrl:1
	v_mul_f32_e32 v106, 0x3db504f3, v106
	s_nop 0
	v_add_f32_dpp v128, v128, v128 row_ror:8 row_mask:0xf bank_mask:0xf bound_ctrl:1
	v_add_f32_e32 v128, 0x358637bd, v128
	v_rsq_f32_e32 v128, v128
	v_pk_mul_f32 v[74:75], v[74:75], v[106:107] op_sel_hi:[1,0]
	v_pk_mul_f32 v[72:73], v[72:73], v[106:107] op_sel_hi:[1,0]
	v_pk_mul_f32 v[78:79], v[78:79], v[106:107] op_sel_hi:[1,0]
	v_pk_mul_f32 v[76:77], v[76:77], v[106:107] op_sel_hi:[1,0]
	ds_write_b128 v120, v[72:75]
	v_pk_mul_f32 v[196:197], v[100:101], v[128:129] op_sel_hi:[1,0]
	v_pk_mul_f32 v[194:195], v[80:81], v[128:129] op_sel_hi:[1,0]
	v_pk_mul_f32 v[104:105], v[104:105], v[128:129] op_sel_hi:[1,0]
	v_pk_mul_f32 v[102:103], v[102:103], v[128:129] op_sel_hi:[1,0]
	v_cvt_pk_bf16_f32 v72, v72, v73
	v_cvt_pk_bf16_f32 v73, v74, v75
	v_cvt_pk_bf16_f32 v74, v76, v77
	v_cvt_pk_bf16_f32 v75, v78, v79
	v_add_u32_e32 v80, s83, v122
	ds_write_b128 v120, v[76:79] offset:16
	ds_write_b128 v120, v[194:197] offset:16896
	ds_write_b128 v120, v[102:105] offset:16912
	ds_write_b128 v121, v[190:193] offset:33792
	v_cvt_pk_bf16_f32 v76, v194, v195
	v_cvt_pk_bf16_f32 v77, v196, v197
	v_cvt_pk_bf16_f32 v78, v102, v103
	v_cvt_pk_bf16_f32 v79, v104, v105
	ds_write_b128 v80, v[72:75]
	v_add_u32_e32 v72, s46, v122
	ds_write_b128 v72, v[76:79]
	s_and_saveexec_b64 s[48:49], s[6:7]
	s_cbranch_execz .LBB0_900
	ds_read_b32 v72, v124
	s_mov_b32 s0, 0xbfb8aa3b
	s_waitcnt lgkmcnt(0)
	v_add_f32_e32 v72, v107, v72
	v_mul_f32_e64 v73, |v72|, s0
	v_exp_f32_e32 v73, v73
	s_mov_b32 s0, 0x800000
	v_max_f32_e32 v72, 0, v72
	v_add_f32_e32 v73, 1.0, v73
	v_cmp_gt_f32_e32 vcc, s0, v73
	s_mov_b32 s0, 0x3f317217
	s_nop 0
	v_cndmask_b32_e64 v74, 0, 32, vcc
	v_ldexp_f32 v73, v73, v74
	v_log_f32_e32 v73, v73
	s_nop 0
	v_mul_f32_e32 v74, 0x3f317217, v73
	v_fma_f32 v74, v73, s0, -v74
	v_fmac_f32_e32 v74, 0x3377d1cf, v73
	s_mov_b32 s0, 0x7f800000
	v_fmac_f32_e32 v74, 0x3f317217, v73
	v_cmp_lt_f32_e64 s[34:35], |v73|, s0
	s_nop 1
	v_cndmask_b32_e64 v73, v73, v74, s[34:35]
	v_cndmask_b32_e32 v74, 0, v243, vcc
	v_sub_f32_e32 v73, v73, v74
	v_add_f32_e32 v72, v72, v73
	v_mul_f32_e64 v72, v72, -v110
	ds_write_b32 v163, v72 offset:41984
	ds_read_b32 v72, v123
	s_waitcnt lgkmcnt(0)
	v_mul_f32_e32 v72, 0xbfb8aa3b, v72
	v_exp_f32_e32 v72, v72
	s_nop 0
	v_add_f32_e32 v72, 1.0, v72
	v_rcp_f32_e32 v72, v72
	ds_write_b32 v163, v72 offset:41988
